# v035
# baseline (speedup 1.0000x reference)
; __device__ __forceinline__ int otid(int wvs) { int l; asm volatile("v_mbcnt_lo_u32_b32 %0, -1, 0\n\tv_mbcnt_hi_u32_b32 %0, -1, %0" : "=v"(l)); return wvs * 64 + l; }
; __device__ __forceinline__ int v_rd_base(int lane) { return ((lane & 3) << 3) | (((lane >> 2) & 3) << 6) | (((lane >> 4) & 1) << 5) | (((lane >> 5) & 1) << 8); }
; #define ISSUE_K(t, slot) do { const char* kg_ = (const char*)(Kh + (long)(t) * (KVBLK * 192)); char* kl_ = K_lds + (slot) * SHM_K + tid * 16; \
;     DMA16(kg_ + kso0, kl_); DMA16(kg_ + kso1, kl_ + 8192); DMA16(kg_ + kso2, kl_ + 16384); } while (0)
; __device__ __forceinline__ void attn_body(const u16* __restrict__ Qb, const u16* __restrict__ Kh, const u16* __restrict__ Vh,
;                                           u16* __restrict__ Ob, int seq, int wvs) {
;     ...
;   const int tid = otid(wvs), wid = tid >> 6, lane = tid & 63, r32 = lane & 31, hi = lane >> 5;
;   char* V_lds = lds; char* K_lds = lds + 3 * SHM_V;
;   float* ws = (float*)(lds + 3 * SHM_V + 3 * SHM_K) + wid * 64; float* li_l = ws; float* al_l = ws + 32;
;   float m_reg = -1e30f, l_reg = 0; f32x16 o[4] = {}; bf16x8 qr[12];
;   const u16* Qw = Qb + (long)(wid * QBLK + r32) * 192 + hi * 8;
; #pragma unroll
;   for (int d0 = 0; d0 < 12; ++d0) qr[d0] = *reinterpret_cast<const bf16x8*>(Qw + d0 * 16);
;   unsigned kso0, kso1, kso2, vso0, vso1;
;   { int p = tid * 16, row = p / 384, pc = p - row * 384; kso0 = row * 384 + (pc ^ (((row >> 1) & 7) << 4));
;     p = 8192 + tid * 16; row = p / 384; pc = p - row * 384; kso1 = row * 384 + (pc ^ (((row >> 1) & 7) << 4));
;     p = 16384 + tid * 16; row = p / 384; pc = p - row * 384; kso2 = row * 384 + (pc ^ (((row >> 1) & 7) << 4)); }
;   { int p = tid * 16, sub = p >> 9, w = p & 511, kk = (sub >> 2) * 8 + (w >> 6), c = (sub & 3) * 32 + ((w & 63) >> 1);
;     int k = (kk & ~0xC) | ((kk & 4) << 1) | ((kk & 8) >> 1); vso0 = k * 256 + c * 2;
;     p = 8192 + tid * 16; sub = p >> 9; w = p & 511; kk = (sub >> 2) * 8 + (w >> 6); c = (sub & 3) * 32 + ((w & 63) >> 1);
;     k = (kk & ~0xC) | ((kk & 4) << 1) | ((kk & 8) >> 1); vso1 = k * 256 + c * 2; }
;   const int vb0 = (int)(uintptr_t)V_lds + v_rd_base(lane);
;     ...
;   f32x16 pA0, pA1, pB0, pB1; float mnA, mnB, alA, alB; bf16x8 pa0, pa1, pa2, pa3; const int NT = seq / KVBLK;
;   ISSUE_K(0, 0); ISSUE_V(0, 0); ISSUE_K(1, 1);
;   TBAR(5);
.LBB0_329:
	s_and_b64 vcc, exec, s[10:11]
	s_cbranch_vccz .LBB0_767
	v_mbcnt_lo_u32_b32 v2, -1, 0
	v_mbcnt_hi_u32_b32 v2, -1, v2
	s_movk_i32 s4, 0xffe0
	v_add_u32_e32 v3, s69, v2
	v_ashrrev_i32_e32 v4, 1, v3
	v_bfi_b32 v5, s4, v4, v2
	v_readlane_b32 s4, v255, 0
	v_readlane_b32 s5, v255, 1
	v_bfe_u32 v186, v2, 5, 1
	v_lshlrev_b32_e32 v160, 4, v186
	v_mov_b64_e32 v[0:1], s[4:5]
	v_mad_i64_i32 v[0:1], s[4:5], v5, s56, v[0:1]
	v_lshl_add_u64 v[0:1], v[0:1], 0, v[160:161]
	s_mov_b32 s4, 0x2aaaaaab
	global_load_dwordx4 v[140:143], v[0:1], off
	global_load_dwordx4 v[136:139], v[0:1], off offset:32
	global_load_dwordx4 v[132:135], v[0:1], off offset:64
	global_load_dwordx4 v[128:131], v[0:1], off offset:96
	global_load_dwordx4 v[124:127], v[0:1], off offset:128
	global_load_dwordx4 v[120:123], v[0:1], off offset:160
	global_load_dwordx4 v[116:119], v[0:1], off offset:192
	global_load_dwordx4 v[112:115], v[0:1], off offset:224
	global_load_dwordx4 v[108:111], v[0:1], off offset:256
	global_load_dwordx4 v[104:107], v[0:1], off offset:288
	global_load_dwordx4 v[100:103], v[0:1], off offset:320
	global_load_dwordx4 v[96:99], v[0:1], off offset:352
	v_mul_hi_i32 v1, v3, s4
	v_lshrrev_b32_e32 v5, 31, v1
	v_ashrrev_i32_e32 v1, 2, v1
	v_add_u32_e32 v1, v1, v5
	v_lshlrev_b32_e32 v0, 4, v3
	v_mul_lo_u32 v5, v1, s56
	v_lshlrev_b32_e32 v1, 3, v1
	v_sub_u32_e32 v6, v0, v5
	v_and_b32_e32 v1, 0x70, v1
	v_xad_u32 v48, v6, v1, v5
	v_add_u32_e32 v1, 0x2000, v0
	v_mul_hi_i32 v5, v1, s4
	v_lshrrev_b32_e32 v6, 31, v5
	v_ashrrev_i32_e32 v5, 6, v5
	v_add_u32_e32 v5, v5, v6
	v_mul_i32_i24_e32 v6, 0x180, v5
	v_lshlrev_b32_e32 v5, 3, v5
	v_sub_u32_e32 v7, v1, v6
	v_and_b32_e32 v5, 0x70, v5
	v_xad_u32 v50, v7, v5, v6
	v_add_u32_e32 v5, 0x4000, v0
	v_mul_hi_i32 v6, v5, s4
	v_lshrrev_b32_e32 v7, 31, v6
	v_ashrrev_i32_e32 v6, 6, v6
	v_add_u32_e32 v6, v6, v7
	v_mul_i32_i24_e32 v7, 0x180, v6
	v_lshlrev_b32_e32 v6, 3, v6
	v_sub_u32_e32 v5, v5, v7
	v_and_b32_e32 v6, 0x70, v6
	v_xad_u32 v52, v5, v6, v7
	v_ashrrev_i32_e32 v5, 4, v3
	v_ashrrev_i32_e32 v1, 8, v1
	v_and_b32_e32 v63, -16, v5
	v_lshrrev_b32_e32 v6, 1, v3
	v_lshrrev_b32_e32 v5, 1, v5
	v_lshrrev_b32_e32 v7, 1, v1
	v_and_b32_e32 v64, 8, v6
	v_and_b32_e32 v65, 4, v5
	v_lshlrev_b32_e32 v6, 1, v3
	v_and_b32_e32 v7, 4, v7
	v_bfe_u32 v62, v3, 2, 2
	v_or_b32_e32 v5, v65, v63
	v_and_b32_e32 v66, 0xc0, v6
	v_and_b32_e32 v67, 48, v0
	v_and_or_b32 v68, v1, -16, v7
	v_or3_b32 v5, v5, v62, v64
	v_or_b32_e32 v6, v67, v66
	v_or3_b32 v1, v68, v62, v64
	v_add_u32_e32 v192, 0, v0
	v_lshl_or_b32 v5, v5, 8, v6
	v_bfe_u32 v252, v5, 10, 1
	v_bfe_u32 v253, v5, 11, 1
	v_xor_b32_e32 v252, v252, v253
	v_mul_u32_u24_e32 v252, 0xc00, v252
	v_xor_b32_e32 v5, v5, v252
	v_lshl_or_b32 v1, v1, 8, v6
	v_bfe_u32 v252, v1, 10, 1
	v_bfe_u32 v253, v1, 11, 1
	v_xor_b32_e32 v252, v252, v253
	v_mul_u32_u24_e32 v252, 0xc00, v252
	v_xor_b32_e32 v1, v1, v252
	v_add_u32_e32 v6, 0xc000, v192
	s_add_i32 s6, 0, 0x1e000
	v_readfirstlane_b32 s5, v6
	v_add_u32_e32 v6, 0xe000, v192
	s_mov_b32 m0, s5
	v_readfirstlane_b32 s5, v6
	v_add_u32_e32 v6, 0x10000, v192
	global_load_lds_dwordx4 v48, s[86:87]
	s_mov_b32 m0, s5
	v_readfirstlane_b32 s5, v6
	global_load_lds_dwordx4 v50, s[86:87]
	s_mov_b32 m0, s5
	v_readfirstlane_b32 s5, v192
	v_add_u32_e32 v6, 0x2000, v192
	s_cmp_lg_u32 0, -1
	global_load_lds_dwordx4 v52, s[86:87]
	s_mov_b32 m0, s5
	v_readfirstlane_b32 s5, v6
	s_cselect_b32 s4, 0, 0
	global_load_lds_dwordx4 v5, s[28:29]
	s_mov_b32 m0, s5
	s_add_i32 s5, 0, 0x12000
	v_add_u32_e32 v6, s5, v0
	v_add_u32_e32 v7, 0x2000, v6
	v_readfirstlane_b32 s5, v6
	global_load_lds_dwordx4 v1, s[28:29]
	s_mov_b32 m0, s5
	v_readfirstlane_b32 s5, v7
	v_add_u32_e32 v6, 0x4000, v6
	global_load_lds_dwordx4 v48, s[54:55]
	s_mov_b32 m0, s5
	v_readfirstlane_b32 s5, v6
	global_load_lds_dwordx4 v50, s[54:55]
	s_mov_b32 m0, s5
	v_and_b32_e32 v69, 63, v2
	global_load_lds_dwordx4 v52, s[54:55]
	v_and_b32_e32 v3, 0x3fffffc0, v3
	v_and_b32_e32 v164, 0xffffffe0, v4
	v_lshlrev_b32_e32 v4, 4, v2
	v_lshl_add_u32 v165, v3, 2, s6
	v_lshlrev_b32_e32 v3, 3, v69
	v_and_b32_e32 v4, 0xc0, v4
	v_lshlrev_b32_e32 v6, 1, v2
	v_and_or_b32 v4, v3, 24, v4
	v_and_b32_e32 v6, 32, v6
	v_and_b32_e32 v3, 0x100, v3
	s_waitcnt vmcnt(5) lgkmcnt(0)
	v_or3_b32 v3, v4, v6, v3
	v_and_b32_e32 v187, 31, v2
	s_mov_b32 s31, 1
	s_mov_b32 s30, 4
	s_mov_b32 s12, 0
	v_add_u32_e32 v190, s4, v3
	v_mov_b32_e32 v49, v161
	v_mov_b32_e32 v51, v161
	v_mov_b32_e32 v53, v161
	s_barrier
; #define ISSUE_K(t, slot) do { const char* kg_ = (const char*)(Kh + (long)(t) * (KVBLK * 192)); char* kl_ = K_lds + (slot) * SHM_K + tid * 16; \
;     DMA16(kg_ + kso0, kl_); DMA16(kg_ + kso1, kl_ + 8192); DMA16(kg_ + kso2, kl_ + 16384); } while (0)
; #define ISSUE_V(t, slot) do { const char* vg_ = (const char*)(Vh + (long)(t) * (KVBLK * 128)); char* vl_ = V_lds + (slot) * SHM_V + tid * 16; \
;     DMA16(vg_ + vso0, vl_); DMA16(vg_ + vso1, vl_ + 8192); } while (0)
; #define TBAR(n) do { asm volatile("s_waitcnt vmcnt(" #n ") lgkmcnt(0)" ::: "memory"); __builtin_amdgcn_s_barrier(); SBAR(); } while (0)
; __device__ __forceinline__ void qkt(f32x16& p0, f32x16& p1, const char* Ks, const bf16x8* qr, int r32, int hi) {
;   p0 = f32x16{}; p1 = f32x16{};
; #pragma unroll
;   for (int d0 = 0; d0 < 12; ++d0) { int cb = (d0 * 16 + hi * 8) * 2;
;     bf16x8 b0 = *reinterpret_cast<const bf16x8*>(Ks + KSWZ(r32, cb));
;     bf16x8 b1 = *reinterpret_cast<const bf16x8*>(Ks + KSWZ(32 + r32, cb));
;     p0 = __builtin_amdgcn_mfma_f32_32x32x16_bf16(b0, qr[d0], p0, 0, 0, 0);
;     p1 = __builtin_amdgcn_mfma_f32_32x32x16_bf16(b1, qr[d0], p1, 0, 0, 0); }
; }
; __device__ __forceinline__ void attn_body(const u16* __restrict__ Qb, const u16* __restrict__ Kh, const u16* __restrict__ Vh,
;                                           u16* __restrict__ Ob, int seq, int wvs) {
;     ...
;   ISSUE_K(0, 0); ISSUE_V(0, 0); ISSUE_K(1, 1);
;   TBAR(5);
;   ISSUE_K(2, 2); ISSUE_V(1, 1);
;   qkt(pA0, pA1, K_lds, qr, r32, hi); partialSM(pA0, pA1, m_reg, mnA, alA);
	v_add_u32_e32 v0, s83, v0
	v_add_u32_e32 v3, 0x2000, v0
	v_readfirstlane_b32 s4, v0
	s_mov_b32 m0, s4
	v_readfirstlane_b32 s4, v3
	v_add_u32_e32 v0, 0x4000, v0
	global_load_lds_dwordx4 v48, s[44:45]
	s_mov_b32 m0, s4
	v_readfirstlane_b32 s4, v0
	v_add_u32_e32 v0, 0x4000, v192
	global_load_lds_dwordx4 v50, s[44:45]
	s_mov_b32 m0, s4
	v_readfirstlane_b32 s4, v0
	v_add_u32_e32 v0, 0x6000, v192
	global_load_lds_dwordx4 v52, s[44:45]
	s_mov_b32 m0, s4
	v_readfirstlane_b32 s4, v0
	v_lshlrev_b32_e32 v0, 3, v2
	v_mul_u32_u24_e32 v8, 0x180, v187
	v_and_b32_e32 v9, 0x70, v0
	global_load_lds_dwordx4 v5, s[50:51]
	s_mov_b32 m0, s4
	v_bitop3_b32 v193, v160, v8, v9 bitop3:0xde
	global_load_lds_dwordx4 v1, s[50:51]
	v_add_u32_e32 v4, 0, v193
	ds_read_b128 v[0:3], v4 offset:49152
	ds_read_b128 v[4:7], v4 offset:61440
	s_waitcnt lgkmcnt(0)
	v_mfma_f32_32x32x16_bf16 v[16:31], v[0:3], v[140:143], 0
	v_or_b32_e32 v0, 32, v160
	v_bitop3_b32 v199, v0, v8, v9 bitop3:0xde
	s_mov_b32 s13, s12
	s_mov_b32 s14, s12
	s_mov_b32 s15, s12
	s_mov_b32 s16, s12
	s_mov_b32 s17, s12
	v_mfma_f32_32x32x16_bf16 v[32:47], v[4:7], v[140:143], 0
	v_add_u32_e32 v4, 0, v199
	ds_read_b128 v[0:3], v4 offset:49152
	ds_read_b128 v[4:7], v4 offset:61440
	s_mov_b32 s18, s12
	s_mov_b32 s19, s12
	s_mov_b32 s20, s12
	s_mov_b32 s21, s12
	s_mov_b32 s22, s12
	s_waitcnt lgkmcnt(1)
	v_mfma_f32_32x32x16_bf16 v[16:31], v[0:3], v[136:139], v[16:31]
	v_or_b32_e32 v0, 64, v160
	v_bitop3_b32 v200, v0, v8, v9 bitop3:0xde
	s_mov_b32 s23, s12
	s_mov_b32 s24, s12
	s_mov_b32 s25, s12
	s_mov_b32 s26, s12
	s_mov_b32 s27, s12
	s_waitcnt lgkmcnt(0)
	v_mfma_f32_32x32x16_bf16 v[32:47], v[4:7], v[136:139], v[32:47]
	v_add_u32_e32 v4, 0, v200
	ds_read_b128 v[0:3], v4 offset:49152
	ds_read_b128 v[4:7], v4 offset:61440
	v_mov_b32_e32 v168, v52
	v_mov_b32_e32 v167, v50
	v_mov_b32_e32 v166, v48
	s_add_u32 s98, s80, s48
	s_addc_u32 s99, s81, s49
	s_add_u32 s98, s98, s70
	s_addc_u32 s99, s99, s71
	v_cmp_gt_u32_e64 s[6:7], 32, v69
	v_lshl_add_u32 v188, v187, 2, v165
	s_waitcnt lgkmcnt(1)
	v_mfma_f32_32x32x16_bf16 v[16:31], v[0:3], v[132:135], v[16:31]
	v_or_b32_e32 v0, 0x60, v160
	v_bitop3_b32 v202, v0, v8, v9 bitop3:0xde
	v_mov_b32_e32 v189, 0
	s_waitcnt lgkmcnt(0)
	v_mfma_f32_32x32x16_bf16 v[32:47], v[4:7], v[132:135], v[32:47]
	v_add_u32_e32 v4, 0, v202
	ds_read_b128 v[0:3], v4 offset:49152
	ds_read_b128 v[4:7], v4 offset:61440
	s_waitcnt lgkmcnt(1)
	v_mfma_f32_32x32x16_bf16 v[16:31], v[0:3], v[128:131], v[16:31]
	v_or_b32_e32 v0, 0x80, v160
	v_xad_u32 v207, v0, v9, v8
	v_add_u32_e32 v10, 0, v207
	s_waitcnt lgkmcnt(0)
	v_mfma_f32_32x32x16_bf16 v[32:47], v[4:7], v[128:131], v[32:47]
	ds_read_b128 v[0:3], v10 offset:49152
	ds_read_b128 v[4:7], v10 offset:61440
	s_waitcnt lgkmcnt(1)
	v_mfma_f32_32x32x16_bf16 v[16:31], v[0:3], v[124:127], v[16:31]
	v_or_b32_e32 v0, 0xa0, v160
	v_xad_u32 v203, v0, v9, v8
	v_add_u32_e32 v10, 0, v203
	s_waitcnt lgkmcnt(0)
	v_mfma_f32_32x32x16_bf16 v[32:47], v[4:7], v[124:127], v[32:47]
	ds_read_b128 v[0:3], v10 offset:49152
	ds_read_b128 v[4:7], v10 offset:61440
	s_waitcnt lgkmcnt(1)
	v_mfma_f32_32x32x16_bf16 v[16:31], v[0:3], v[120:123], v[16:31]
	v_or_b32_e32 v0, 0xc0, v160
	v_xad_u32 v201, v0, v9, v8
	v_add_u32_e32 v10, 0, v201
	s_waitcnt lgkmcnt(0)
	v_mfma_f32_32x32x16_bf16 v[32:47], v[4:7], v[120:123], v[32:47]
	ds_read_b128 v[0:3], v10 offset:49152
	ds_read_b128 v[4:7], v10 offset:61440
	s_waitcnt lgkmcnt(1)
	v_mfma_f32_32x32x16_bf16 v[16:31], v[0:3], v[116:119], v[16:31]
	v_or_b32_e32 v0, 0xe0, v160
	v_xad_u32 v198, v0, v9, v8
	v_add_u32_e32 v10, 0, v198
	s_waitcnt lgkmcnt(0)
	v_mfma_f32_32x32x16_bf16 v[32:47], v[4:7], v[116:119], v[32:47]
	ds_read_b128 v[0:3], v10 offset:49152
	ds_read_b128 v[4:7], v10 offset:61440
	s_waitcnt lgkmcnt(1)
	v_mfma_f32_32x32x16_bf16 v[16:31], v[0:3], v[112:115], v[16:31]
	v_or_b32_e32 v0, 0x100, v160
	v_xad_u32 v197, v0, v9, v8
	v_add_u32_e32 v10, 0, v197
	s_waitcnt lgkmcnt(0)
	v_mfma_f32_32x32x16_bf16 v[32:47], v[4:7], v[112:115], v[32:47]
	ds_read_b128 v[0:3], v10 offset:49152
	ds_read_b128 v[4:7], v10 offset:61440
	s_waitcnt lgkmcnt(1)
	v_mfma_f32_32x32x16_bf16 v[16:31], v[0:3], v[108:111], v[16:31]
	v_or_b32_e32 v0, 0x120, v160
	v_xad_u32 v196, v0, v9, v8
	v_add_u32_e32 v10, 0, v196
	ds_read_b128 v[0:3], v10 offset:49152
	s_waitcnt lgkmcnt(1)
	v_mfma_f32_32x32x16_bf16 v[32:47], v[4:7], v[108:111], v[32:47]
	ds_read_b128 v[4:7], v10 offset:61440
	s_waitcnt lgkmcnt(1)
	v_mfma_f32_32x32x16_bf16 v[16:31], v[0:3], v[104:107], v[16:31]
	v_or_b32_e32 v0, 0x140, v160
	v_xad_u32 v195, v0, v9, v8
	v_add_u32_e32 v10, 0, v195
	ds_read_b128 v[0:3], v10 offset:49152
	ds_read_b128 v[54:57], v10 offset:61440
	s_waitcnt lgkmcnt(2)
	v_mfma_f32_32x32x16_bf16 v[32:47], v[4:7], v[104:107], v[32:47]
	v_or_b32_e32 v4, 0x160, v160
	v_xad_u32 v194, v4, v9, v8
	v_add_u32_e32 v8, 0, v194
	ds_read_b128 v[4:7], v8 offset:49152
	ds_read_b128 v[58:61], v8 offset:61440
	s_waitcnt lgkmcnt(3)
; __device__ __forceinline__ void partialSM(f32x16& p0, f32x16& p1, float& m_reg, float& mn, float& alpha) {
;   constexpr float C = ASCALE * 1.4426950408889634f;
;   float pmax = p0[0]; for (int r = 1; r < 16; ++r) pmax = fmaxf(pmax, p0[r]); for (int r = 0; r < 16; ++r) pmax = fmaxf(pmax, p1[r]);
;   { auto rr = __builtin_amdgcn_permlane32_swap(__float_as_uint(pmax), __float_as_uint(pmax), false, false);
;     pmax = fmaxf(__uint_as_float(rr[0]), __uint_as_float(rr[1])); }
;   if (__builtin_expect(__all(pmax - m_reg <= THR / ASCALE), 1)) { mn = m_reg; alpha = 1.f; }
;   else { mn = fmaxf(m_reg, pmax); alpha = __builtin_amdgcn_exp2f((m_reg - mn) * C); m_reg = mn; }
;   float mnC = -mn * C;
;   for (int r = 0; r < 16; ++r) p0[r] = fmaf(p0[r], C, mnC); for (int r = 0; r < 16; ++r) p1[r] = fmaf(p1[r], C, mnC);
;   for (int r = 0; r < 16; ++r) p0[r] = __builtin_amdgcn_exp2f(p0[r]);
; }
	v_mfma_f32_32x32x16_bf16 v[16:31], v[0:3], v[100:103], v[16:31]
	s_waitcnt lgkmcnt(1)
	v_mfma_f32_32x32x16_bf16 v[16:31], v[4:7], v[96:99], v[16:31]
	v_mov_b64_e32 v[0:1], s[12:13]
	v_mov_b64_e32 v[14:15], s[26:27]
	v_mov_b64_e32 v[2:3], s[14:15]
	v_mov_b64_e32 v[4:5], s[16:17]
	v_mov_b64_e32 v[6:7], s[18:19]
	v_mov_b64_e32 v[8:9], s[20:21]
	v_mov_b64_e32 v[10:11], s[22:23]
	v_mfma_f32_32x32x16_bf16 v[32:47], v[54:57], v[100:103], v[32:47]
	s_nop 3
	v_max_f32_e32 v70, v17, v17
	v_max_f32_e32 v71, v16, v16
	v_max_f32_e32 v70, v71, v70
	v_max3_f32 v54, v70, v18, v19
	v_max3_f32 v54, v54, v20, v21
	v_max3_f32 v54, v54, v22, v23
	v_max3_f32 v54, v54, v24, v25
	s_waitcnt lgkmcnt(0)
	v_mfma_f32_32x32x16_bf16 v[32:47], v[58:61], v[96:99], v[32:47]
	v_max3_f32 v54, v54, v26, v27
	v_max3_f32 v54, v54, v28, v29
	v_max3_f32 v54, v54, v30, v31
	v_mov_b64_e32 v[12:13], s[24:25]
	s_nop 7
	v_max3_f32 v54, v54, v32, v33
	v_max3_f32 v54, v54, v34, v35
	v_max3_f32 v54, v54, v36, v37
	v_max3_f32 v54, v54, v38, v39
	v_max3_f32 v54, v54, v40, v41
	v_max3_f32 v54, v54, v42, v43
	v_max3_f32 v54, v54, v44, v45
	v_max3_f32 v54, v54, v46, v47
	v_mov_b32_e32 v55, v54
	s_nop 1
	v_permlane32_swap_b32_e32 v54, v55
	v_max_f32_e32 v55, v55, v55
	v_max_f32_e32 v54, v54, v54
	v_max_f32_e32 v54, v54, v55
	v_add_f32_e32 v55, 0x7149f2ca, v54
	v_cmp_ge_f32_e32 vcc, s35, v55
	s_cmp_eq_u64 vcc, exec
	v_max_f32_e32 v54, 0xf149f2ca, v54
	s_cselect_b64 vcc, -1, 0
	v_mov_b32_e32 v55, 0xf149f2ca
	v_cndmask_b32_e32 v191, v54, v55, vcc
	v_sub_f32_e32 v56, 0xf149f2ca, v54
	v_mul_f32_e32 v54, 0xbdd53b94, v191
	v_fmamk_f32 v16, v16, 0x3dd53b94, v54
	v_exp_f32_e32 v218, v16
	v_fmamk_f32 v16, v17, 0x3dd53b94, v54
	v_exp_f32_e32 v220, v16
	v_fmamk_f32 v16, v18, 0x3dd53b94, v54
	v_exp_f32_e32 v221, v16
	v_fmamk_f32 v16, v19, 0x3dd53b94, v54
	v_exp_f32_e32 v222, v16
	v_fmamk_f32 v16, v20, 0x3dd53b94, v54
	v_exp_f32_e32 v223, v16
	v_fmamk_f32 v16, v21, 0x3dd53b94, v54
	v_exp_f32_e32 v225, v16
	v_fmamk_f32 v16, v22, 0x3dd53b94, v54
	v_exp_f32_e32 v224, v16
	v_fmamk_f32 v16, v23, 0x3dd53b94, v54
	v_exp_f32_e32 v226, v16
	v_fmamk_f32 v16, v24, 0x3dd53b94, v54
	v_exp_f32_e32 v211, v16
	v_fmamk_f32 v16, v25, 0x3dd53b94, v54
	v_exp_f32_e32 v212, v16
	v_fmamk_f32 v16, v26, 0x3dd53b94, v54
	v_exp_f32_e32 v213, v16
	v_fmamk_f32 v16, v27, 0x3dd53b94, v54
	v_exp_f32_e32 v215, v16
	v_fmamk_f32 v16, v28, 0x3dd53b94, v54
	v_exp_f32_e32 v214, v16
	v_fmamk_f32 v16, v29, 0x3dd53b94, v54
	v_exp_f32_e32 v216, v16
	v_fmamk_f32 v16, v30, 0x3dd53b94, v54
	v_exp_f32_e32 v217, v16
	v_or3_b32 v16, v68, v64, v62
	v_lshlrev_b32_e32 v16, 8, v16
	v_mul_f32_e32 v56, 0x3dd53b94, v56
	v_or3_b32 v16, v16, v66, v67
	v_mov_b32_e32 v17, v161
	v_exp_f32_e32 v56, v56
	v_bfe_u32 v252, v16, 10, 1
	v_bfe_u32 v253, v16, 11, 1
	v_xor_b32_e32 v252, v252, v253
	v_mul_u32_u24_e32 v252, 0xc00, v252
	v_xor_b32_e32 v16, v16, v252
	v_mov_b32_e32 v170, v16
	s_add_u32 s100, s80, s88
	s_addc_u32 s101, s81, s89
	s_add_u32 s100, s100, s72
	s_addc_u32 s101, s101, s73
	v_or_b32_e32 v16, v63, v64
	v_pk_fma_f32 v[144:145], v[46:47], s[68:69], v[54:55] op_sel_hi:[1,0,0]
	v_pk_fma_f32 v[146:147], v[44:45], s[68:69], v[54:55] op_sel_hi:[1,0,0]
	v_pk_fma_f32 v[148:149], v[42:43], s[68:69], v[54:55] op_sel_hi:[1,0,0]
	v_pk_fma_f32 v[150:151], v[40:41], s[68:69], v[54:55] op_sel_hi:[1,0,0]
	v_pk_fma_f32 v[152:153], v[38:39], s[68:69], v[54:55] op_sel_hi:[1,0,0]
	v_pk_fma_f32 v[154:155], v[36:37], s[68:69], v[54:55] op_sel_hi:[1,0,0]
	v_pk_fma_f32 v[156:157], v[34:35], s[68:69], v[54:55] op_sel_hi:[1,0,0]
	v_pk_fma_f32 v[158:159], v[32:33], s[68:69], v[54:55] op_sel_hi:[1,0,0]
	v_fmac_f32_e32 v54, 0x3dd53b94, v31
	v_or3_b32 v16, v16, v65, v62
	v_exp_f32_e32 v219, v54
	v_lshlrev_b32_e32 v16, 8, v16
	v_or3_b32 v16, v16, v66, v67
	v_cndmask_b32_e64 v208, v56, 1.0, vcc
	v_bfe_u32 v252, v16, 10, 1
	v_bfe_u32 v253, v16, 11, 1
	v_xor_b32_e32 v252, v252, v253
	v_mul_u32_u24_e32 v252, 0xc00, v252
	v_xor_b32_e32 v16, v16, v252
	v_mov_b32_e32 v169, v16
	v_mov_b64_e32 v[62:63], v[14:15]
	v_mov_b64_e32 v[46:47], v[14:15]
	v_mov_b64_e32 v[30:31], v[14:15]
	v_mov_b64_e32 v[60:61], v[12:13]
	v_mov_b64_e32 v[58:59], v[10:11]
	v_mov_b64_e32 v[56:57], v[8:9]
	v_mov_b64_e32 v[54:55], v[6:7]
	v_mov_b64_e32 v[52:53], v[4:5]
	v_mov_b64_e32 v[50:51], v[2:3]
	v_mov_b64_e32 v[48:49], v[0:1]
	v_mov_b64_e32 v[44:45], v[12:13]
	v_mov_b64_e32 v[42:43], v[10:11]
	v_mov_b64_e32 v[40:41], v[8:9]
	v_mov_b64_e32 v[38:39], v[6:7]
	v_mov_b64_e32 v[36:37], v[4:5]
	v_mov_b64_e32 v[34:35], v[2:3]
	v_mov_b64_e32 v[32:33], v[0:1]
	v_mov_b64_e32 v[28:29], v[12:13]
	v_mov_b64_e32 v[26:27], v[10:11]
	v_mov_b64_e32 v[24:25], v[8:9]
	v_mov_b64_e32 v[22:23], v[6:7]
	v_mov_b64_e32 v[20:21], v[4:5]
	v_mov_b64_e32 v[18:19], v[2:3]
	v_mov_b64_e32 v[16:17], v[0:1]
